# static s_setprio 1 for waves 4-7 during attention units (reset at unit end)
# baseline (speedup 1.0000x reference)
; __device__ __forceinline__ void m2_phase(const Args& c, int l, LAS unsigned char* lds, int G, int mode, bool dry, int cidx) {
;     ...
;         for (;;) {
;             __syncthreads();
;             if (tid_ == 0) *slot = (int)atomicAdd(ctr, 1u);
;             __syncthreads();
;             const int q = *slot;
;             if (q >= 128) break;
;             const int qb = 15 - (q >> 3);
;             attn_unit(c, l, q & 7, qx, qb, lam, lam_init, lds);
;         }
.LBB0_240:
	s_setprio 0
	s_and_b64 vcc, exec, s[2:3]
	s_cbranch_vccnz .LBB0_237

; __device__ __forceinline__ void unpack8(u32x4v w, float* f) { f[0] = bflo(w.x); f[1] = bfhi(w.x); f[2] = bflo(w.y); f[3] = bfhi(w.y); f[4] = bflo(w.z); f[5] = bfhi(w.z); f[6] = bflo(w.w); f[7] = bfhi(w.w); }
; __device__ __forceinline__ void attn_unit(const Args& c, int l, int b, int h, int qb, float lam, float lam_init, LAS unsigned char* lds) {
;     ...
;         const bf16* qrow = P + (seq0 + 128 * qb + 16 * w + r) * PW + QC;
; #pragma unroll
;         for (int m = 0; m < 2; ++m) {
;             float f[16];
;             unpack8(*(const u32x4v*)(qrow + m * 64 + q4 * 8), f); unpack8(*(const u32x4v*)(qrow + m * 64 + 32 + q4 * 8), f + 8);
;             float ss = 0.f;
; #pragma unroll
;             for (int e = 0; e < 16; ++e) ss += f[e] * f[e];
;             ss += __shfl_xor(ss, 16); ss += __shfl_xor(ss, 32);
; __device__ __forceinline__ void m2_phase(const Args& c, int l, LAS unsigned char* lds, int G, int mode, bool dry, int cidx) {
;     ...
;             __syncthreads();
;             if (tid_ == 0) *slot = (int)atomicAdd(ctr, 1u);
;             __syncthreads();
;             const int q = *slot;
;             if (q >= 128) break;
;             const int qb = 15 - (q >> 3);
;             attn_unit(c, l, q & 7, qx, qb, lam, lam_init, lds);
.LBB0_243:
	s_or_b64 exec, exec, s[2:3]
	v_mov_b32_e32 v0, s39
	s_waitcnt lgkmcnt(0)
	s_barrier
	ds_read_b32 v0, v0
	s_movk_i32 s2, 0x7f
	s_waitcnt lgkmcnt(0)
	v_cmp_lt_i32_e32 vcc, s2, v0
	v_readfirstlane_b32 s4, v0
	s_mov_b64 s[2:3], -1
	s_cbranch_vccnz .LBB0_240
	v_readlane_b32 s8, v252, 57
	s_and_b32 s6, s4, 7
	s_lshr_b32 s7, s4, 6
	s_lshl_b32 s7, s7, 3
	s_add_i32 s6, s6, s7
	v_readlane_b32 s10, v252, 59
	v_readlane_b32 s11, v252, 60
	s_sub_i32 s22, 15, s6
	v_mov_b32_e32 v106, v179
	s_mov_b64 s[38:39], s[10:11]
	v_readlane_b32 s9, v252, 58
	s_mov_b32 s8, 0
	s_add_u32 s2, s38, 0xa800000
	s_addc_u32 s3, s39, 0
	s_lshl_b32 s4, s4, 8
	s_ashr_i32 s9, s8, 31
	s_and_b32 s18, s4, 0x3800
	s_lshl_b64 s[4:5], s[8:9], 3
	v_readlane_b32 s8, v251, 0
	v_readlane_b32 s9, v251, 1
	s_add_u32 s24, s8, s4
	s_addc_u32 s25, s9, s5
	s_load_dwordx4 s[8:11], s[24:25], 0xb0
	v_readfirstlane_b32 s4, v106
	v_and_b32_e32 v107, 15, v106
	v_mov_b64_e32 v[18:19], s[2:3]
	v_bfe_u32 v108, v106, 4, 2
	s_waitcnt lgkmcnt(0)
	s_cmp_lt_u32 s4, 0x100
	s_cbranch_scc1 .Lattn_prio_skip
	s_setprio 1
.Lattn_prio_skip:
	s_add_u32 s12, s8, s30
	s_addc_u32 s13, s9, s31
	s_ashr_i32 s4, s4, 2
	s_lshl_b32 s7, s22, 7
	s_and_b32 s8, s4, -16
	s_add_i32 s5, s7, s18
	s_ashr_i32 s4, s8, 31
	s_add_u32 s5, s8, s5
	v_or_b32_e32 v184, s5, v107
	s_addc_u32 s9, s4, 0
	v_mad_u64_u32 v[2:3], s[4:5], v184, s27, v[18:19]
	v_mad_i32_i24 v3, s9, v196, v3
	s_lshl_b32 s4, s19, 1
	s_mov_b32 s5, s15
	v_lshl_add_u64 v[2:3], v[2:3], 0, s[4:5]
	v_lshlrev_b32_e32 v0, 4, v108
	v_lshl_add_u64 v[2:3], v[2:3], 0, v[0:1]
	s_movk_i32 s5, 0x1000
	v_add_co_u32_e32 v2, vcc, s5, v2
	v_lshlrev_b32_e32 v14, 5, v108
	s_nop 0
	v_addc_co_u32_e32 v3, vcc, 0, v3, vcc
	flat_load_dwordx4 v[26:29], v[2:3] offset:3904
	flat_load_dwordx4 v[30:33], v[2:3] offset:4032
	flat_load_dwordx4 v[34:37], v[2:3] offset:3840
	flat_load_dwordx4 v[38:41], v[2:3] offset:3968
	s_nop 0
	global_load_dwordx4 v[2:5], v14, s[12:13] offset:144
	global_load_dwordx4 v[6:9], v14, s[12:13] offset:128
	global_load_dwordx4 v[10:13], v14, s[12:13] offset:16
	s_nop 0
	global_load_dwordx4 v[14:17], v14, s[12:13]
	v_ashrrev_i32_e32 v186, 3, v106
	s_lshl_b32 s20, s0, 1
	s_mov_b32 s21, s15
	s_lshl_b32 s28, s1, 1
	s_mov_b32 s29, s15
	s_add_u32 s10, s10, s30
	s_addc_u32 s11, s11, s31
	v_lshlrev_b32_e32 v208, 2, v108
	s_add_i32 s8, s8, s7
	s_movk_i32 s7, 0x110
	v_or_b32_e32 v209, s8, v107
	v_mov_b32_e32 v108, v1
	v_mov_b32_e32 v109, v1
	s_mov_b32 s5, 0
	v_mov_b32_e32 v185, s9
	v_ashrrev_i32_e32 v187, 31, v186
	s_sub_i32 s34, 16, s6
	v_mov_b32_e32 v216, 0
	v_mov_b32_e32 v192, 0xff800000
	v_mov_b32_e32 v148, 0xff800000
	v_mov_b32_e32 v215, 0
	s_mov_b32 s35, 0
	s_waitcnt vmcnt(0) lgkmcnt(0)
	v_lshlrev_b32_e32 v42, 16, v29
	v_and_b32_e32 v43, 0xffff0000, v29
	v_lshlrev_b32_e32 v20, 16, v33
	v_and_b32_e32 v21, 0xffff0000, v33
	v_lshlrev_b32_e32 v44, 16, v28
	v_and_b32_e32 v45, 0xffff0000, v28
	v_lshlrev_b32_e32 v22, 16, v32
	v_and_b32_e32 v23, 0xffff0000, v32
	v_lshlrev_b32_e32 v28, 16, v27
	v_and_b32_e32 v29, 0xffff0000, v27
	v_lshlrev_b32_e32 v24, 16, v31
	v_and_b32_e32 v25, 0xffff0000, v31
	v_lshlrev_b32_e32 v32, 16, v26
	v_and_b32_e32 v33, 0xffff0000, v26
	v_lshlrev_b32_e32 v26, 16, v30
	v_and_b32_e32 v27, 0xffff0000, v30
	v_lshlrev_b32_e32 v30, 16, v37
	v_and_b32_e32 v31, 0xffff0000, v37
	v_lshlrev_b32_e32 v46, 16, v41
	v_and_b32_e32 v47, 0xffff0000, v41
	v_lshlrev_b32_e32 v48, 16, v36
	v_and_b32_e32 v49, 0xffff0000, v36
	v_lshlrev_b32_e32 v36, 16, v40
	v_and_b32_e32 v37, 0xffff0000, v40
	v_lshlrev_b32_e32 v40, 16, v35
	v_and_b32_e32 v41, 0xffff0000, v35
	v_and_b32_e32 v51, 0xffff0000, v34
	v_and_b32_e32 v35, 0xffff0000, v38
	v_lshlrev_b32_e32 v50, 16, v34
	v_lshlrev_b32_e32 v34, 16, v38
	v_mov_b32_e32 v82, v35
	v_mov_b32_e32 v83, v51
	v_lshlrev_b32_e32 v58, 16, v39
	v_mov_b32_e32 v80, v34
	v_mov_b32_e32 v81, v50
	v_pk_mul_f32 v[82:83], v[82:83], v[82:83]
	v_and_b32_e32 v59, 0xffff0000, v39
	v_mov_b32_e32 v76, v58
	v_mov_b32_e32 v77, v40
	v_pk_fma_f32 v[80:81], v[80:81], v[80:81], v[82:83]
	v_mov_b32_e32 v78, v59
	v_mov_b32_e32 v79, v41
	v_pk_fma_f32 v[76:77], v[76:77], v[76:77], v[80:81]
	v_mov_b32_e32 v72, v36
	v_mov_b32_e32 v73, v48
	v_pk_fma_f32 v[76:77], v[78:79], v[78:79], v[76:77]
	v_mov_b32_e32 v74, v37
	v_mov_b32_e32 v75, v49
	v_pk_fma_f32 v[72:73], v[72:73], v[72:73], v[76:77]
	v_mov_b32_e32 v68, v46
	v_mov_b32_e32 v69, v30
	v_pk_fma_f32 v[72:73], v[74:75], v[74:75], v[72:73]
	v_pk_mul_f32 v[64:65], v[32:33], v[32:33]
	v_pk_mul_f32 v[66:67], v[26:27], v[26:27]
	v_mov_b32_e32 v70, v47
	v_mov_b32_e32 v71, v31
	v_pk_fma_f32 v[68:69], v[68:69], v[68:69], v[72:73]
	v_pk_mul_f32 v[60:61], v[28:29], v[28:29]
	v_pk_fma_f32 v[68:69], v[70:71], v[70:71], v[68:69]
	v_mov_b32_e32 v70, v66
	v_mov_b32_e32 v71, v64
	v_pk_mul_f32 v[62:63], v[24:25], v[24:25]
	v_pk_add_f32 v[68:69], v[70:71], v[68:69]
	v_mov_b32_e32 v64, v67
	v_pk_add_f32 v[64:65], v[64:65], v[68:69]
	v_mov_b32_e32 v66, v62
	v_mov_b32_e32 v67, v60
	v_pk_mul_f32 v[54:55], v[44:45], v[44:45]
	v_pk_mul_f32 v[56:57], v[22:23], v[22:23]
	v_pk_add_f32 v[64:65], v[66:67], v[64:65]
	v_mov_b32_e32 v60, v63
	v_pk_add_f32 v[60:61], v[60:61], v[64:65]
	v_mov_b32_e32 v62, v56
	v_mov_b32_e32 v63, v54
	v_pk_mul_f32 v[38:39], v[42:43], v[42:43]
	v_pk_mul_f32 v[52:53], v[20:21], v[20:21]
	v_pk_add_f32 v[60:61], v[62:63], v[60:61]
	v_mov_b32_e32 v54, v57
	v_pk_add_f32 v[54:55], v[54:55], v[60:61]
	v_mov_b32_e32 v56, v52
	v_mov_b32_e32 v57, v38
	v_pk_add_f32 v[54:55], v[56:57], v[54:55]
	v_mov_b32_e32 v38, v53
	v_pk_add_f32 v[38:39], v[38:39], v[54:55]
	ds_bpermute_b32 v53, v205, v39
	ds_bpermute_b32 v52, v205, v38
	s_waitcnt lgkmcnt(0)
; __device__ __forceinline__ unsigned pk2(float lo, float hi) { f32x2_t v = {lo, hi}; bf16x2_t b = __builtin_convertvector(v, bf16x2_t); return __builtin_bit_cast(unsigned, b); }
; #define ATT_FETCH(KT) do { _Pragma("unroll") for (int hh = 0; hh < 2; ++hh) { const bf16* krow = P + (seq0 + 128 * (KT) + 64 * hh + skey) * PW; \
;         gk0[hh] = *(const u32x4v*)(krow + KC + part * 16); gk1[hh] = *(const u32x4v*)(krow + KC + part * 16 + 8); \
;         gv0[hh] = *(const u32x4v*)(krow + VC + part * 16); gv1[hh] = *(const u32x4v*)(krow + VC + part * 16 + 8); } } while (0)
; __device__ __forceinline__ void attn_unit(const Args& c, int l, int b, int h, int qb, float lam, float lam_init, LAS unsigned char* lds) {
;     ...
;             ss += __shfl_xor(ss, 16); ss += __shfl_xor(ss, 32);
;             const float sc = rsqrtf(ss * (1.f / 64.f) + 1e-6f) * (0.125f * 1.4426950408889634f);
; #pragma unroll
;             for (int ks = 0; ks < 2; ++ks) { u32x4v o; const float* g = f + 8 * ks; const float* wn = qnw + ks * 32 + q4 * 8;
;                 o.x = pk2(g[0] * sc * wn[0], g[1] * sc * wn[1]); o.y = pk2(g[2] * sc * wn[2], g[3] * sc * wn[3]); o.z = pk2(g[4] * sc * wn[4], g[5] * sc * wn[5]); o.w = pk2(g[6] * sc * wn[6], g[7] * sc * wn[7]);
;                 qf[m][ks] = __builtin_bit_cast(bf16x8, o); }
;         }
;     }
;     f32x4 O[2][8];
; #pragma unroll
;     for (int m = 0; m < 2; ++m)
; #pragma unroll
;         for (int vb = 0; vb < 8; ++vb) O[m][vb] = (f32x4){0.f, 0.f, 0.f, 0.f};
;     float mrow[2] = {-INFINITY, -INFINITY}, lrow[2] = {0.f, 0.f};
;     const int NT = qb + 1;
;     const int skey = tid >> 3, part = tid & 7;
;     const float* kwp = knw + (part & 3) * 16;
;     u32x4v gk0[2], gk1[2], gv0[2], gv1[2];
;     ...
;     ATT_FETCH(0);
	v_pk_add_f32 v[38:39], v[38:39], v[52:53]
	ds_bpermute_b32 v53, v206, v39
	ds_bpermute_b32 v52, v206, v38
	s_waitcnt lgkmcnt(0)
	v_pk_add_f32 v[38:39], v[38:39], v[52:53]
	s_nop 0
	v_pk_fma_f32 v[38:39], v[38:39], s[26:27], v[178:179] op_sel_hi:[1,0,0]
	s_nop 0
	v_mul_f32_e32 v52, 0x4b800000, v39
	v_cmp_gt_f32_e32 vcc, s33, v39
	s_nop 1
	v_cndmask_b32_e32 v39, v39, v52, vcc
	v_rsq_f32_e32 v39, v39
	s_nop 0
	v_mul_f32_e32 v52, 0x45800000, v39
	v_cndmask_b32_e32 v39, v39, v52, vcc
	v_mul_f32_e32 v52, 0x3e38aa3b, v39
	v_pk_mul_f32 v[28:29], v[52:53], v[28:29] op_sel_hi:[0,1]
	v_pk_mul_f32 v[32:33], v[52:53], v[32:33] op_sel_hi:[0,1]
	v_pk_mul_f32 v[28:29], v[8:9], v[28:29]
	v_pk_mul_f32 v[60:61], v[52:53], v[50:51] op_sel_hi:[0,1]
	v_pk_mul_f32 v[30:31], v[52:53], v[30:31] op_sel_hi:[0,1]
	v_pk_mul_f32 v[42:43], v[52:53], v[42:43] op_sel_hi:[0,1]
	v_cvt_pk_bf16_f32 v51, v28, v29
	v_pk_mul_f32 v[28:29], v[6:7], v[32:33]
	v_pk_mul_f32 v[48:49], v[52:53], v[48:49] op_sel_hi:[0,1]
	v_pk_mul_f32 v[44:45], v[52:53], v[44:45] op_sel_hi:[0,1]
	v_pk_mul_f32 v[42:43], v[4:5], v[42:43]
	v_cvt_pk_bf16_f32 v50, v28, v29
	v_pk_mul_f32 v[28:29], v[12:13], v[30:31]
	v_lshlrev_b32_e32 v30, 4, v106
	v_add_u32_e32 v39, s18, v186
	v_pk_mul_f32 v[40:41], v[52:53], v[40:41] op_sel_hi:[0,1]
	v_cvt_pk_bf16_f32 v53, v42, v43
	v_pk_mul_f32 v[42:43], v[2:3], v[44:45]
	v_cvt_pk_bf16_f32 v57, v28, v29
	v_pk_mul_f32 v[28:29], v[10:11], v[48:49]
	v_and_b32_e32 v30, 0x70, v30
	v_mad_i64_i32 v[32:33], s[12:13], v39, s27, v[18:19]
	v_cvt_pk_bf16_f32 v52, v42, v43
	v_cvt_pk_bf16_f32 v56, v28, v29
	v_pk_mul_f32 v[28:29], v[16:17], v[40:41]
	v_lshl_add_u64 v[40:41], v[32:33], 0, s[20:21]
	v_lshlrev_b32_e32 v42, 1, v30
	v_mov_b32_e32 v43, v1
	v_lshl_add_u64 v[32:33], v[32:33], 0, s[28:29]
	v_lshl_add_u64 v[40:41], v[40:41], 0, v[42:43]
	v_lshl_add_u64 v[32:33], v[32:33], 0, v[42:43]
	flat_load_dwordx4 v[66:69], v[40:41]
	flat_load_dwordx4 v[70:73], v[40:41] offset:16
	flat_load_dwordx4 v[78:81], v[32:33]
	flat_load_dwordx4 v[82:85], v[32:33] offset:16
	v_add_u32_e32 v32, 64, v39
	v_mad_i64_i32 v[18:19], s[12:13], v32, s27, v[18:19]
	v_lshl_add_u64 v[32:33], v[18:19], 0, s[20:21]
	v_lshl_add_u64 v[18:19], v[18:19], 0, s[28:29]
	v_lshl_add_u64 v[32:33], v[32:33], 0, v[42:43]
	v_lshl_add_u64 v[18:19], v[18:19], 0, v[42:43]
	flat_load_dwordx4 v[90:93], v[32:33]
	flat_load_dwordx4 v[94:97], v[32:33] offset:16
	flat_load_dwordx4 v[98:101], v[18:19]
	flat_load_dwordx4 v[102:105], v[18:19] offset:16
	v_mul_f32_e32 v31, 0x4b800000, v38
	v_cmp_gt_f32_e32 vcc, s33, v38
	v_cvt_pk_bf16_f32 v55, v28, v29
	s_nop 0
	v_cndmask_b32_e32 v18, v38, v31, vcc
	v_rsq_f32_e32 v31, v18
	v_pk_mul_f32 v[18:19], v[14:15], v[60:61]
	s_nop 0
	v_cvt_pk_bf16_f32 v54, v18, v19
	v_mul_f32_e32 v18, 0x45800000, v31
	v_cndmask_b32_e32 v18, v31, v18, vcc
	v_mul_f32_e32 v18, 0x3e38aa3b, v18
	v_pk_mul_f32 v[28:29], v[18:19], v[34:35] op_sel_hi:[0,1]
	v_pk_mul_f32 v[14:15], v[14:15], v[28:29]
	s_nop 0
	v_cvt_pk_bf16_f32 v74, v14, v15
	v_pk_mul_f32 v[14:15], v[18:19], v[58:59] op_sel_hi:[0,1]
	v_pk_mul_f32 v[14:15], v[16:17], v[14:15]
	s_nop 0
	v_cvt_pk_bf16_f32 v75, v14, v15
	v_pk_mul_f32 v[14:15], v[18:19], v[36:37] op_sel_hi:[0,1]
	v_pk_mul_f32 v[10:11], v[10:11], v[14:15]
	s_nop 0
	v_cvt_pk_bf16_f32 v76, v10, v11
	v_pk_mul_f32 v[10:11], v[18:19], v[46:47] op_sel_hi:[0,1]
	v_pk_mul_f32 v[10:11], v[12:13], v[10:11]
	s_nop 0
	v_cvt_pk_bf16_f32 v77, v10, v11
	v_pk_mul_f32 v[10:11], v[18:19], v[26:27] op_sel_hi:[0,1]
	v_pk_mul_f32 v[6:7], v[6:7], v[10:11]
	s_nop 0
	v_cvt_pk_bf16_f32 v86, v6, v7
	v_pk_mul_f32 v[6:7], v[18:19], v[24:25] op_sel_hi:[0,1]
	v_pk_mul_f32 v[6:7], v[8:9], v[6:7]
	s_nop 0
	v_cvt_pk_bf16_f32 v87, v6, v7
	v_pk_mul_f32 v[6:7], v[18:19], v[22:23] op_sel_hi:[0,1]
	v_pk_mul_f32 v[2:3], v[2:3], v[6:7]
	s_nop 0
	v_cvt_pk_bf16_f32 v88, v2, v3
	v_pk_mul_f32 v[2:3], v[18:19], v[20:21] op_sel_hi:[0,1]
	v_pk_mul_f32 v[2:3], v[4:5], v[2:3]
	s_nop 0
	v_cvt_pk_bf16_f32 v89, v2, v3
	v_lshlrev_b32_e32 v2, 6, v106
	v_and_b32_e32 v2, 0xc0, v2
	v_mov_b32_e32 v3, v1
	v_lshl_add_u64 v[188:189], s[10:11], 0, v[2:3]
	v_bfe_u32 v2, v106, 2, 2
	v_add_u32_e32 v3, 0, v0
	v_or_b32_e32 v0, v208, v2
	v_lshlrev_b32_e32 v2, 3, v106
	v_mul_u32_u24_e32 v0, 0x110, v0
	v_and_b32_e32 v2, 24, v2
	v_add3_u32 v210, 0, v0, v2
	v_mul_lo_u32 v0, v186, s7
	v_mul_u32_u24_e32 v2, 0x110, v107
	v_mov_b32_e32 v106, v1
	v_mov_b32_e32 v107, v1
	v_add3_u32 v211, 0, v42, v0
	v_lshlrev_b32_e32 v0, 1, v30
	v_add_u32_e32 v212, v3, v2
	v_mov_b64_e32 v[2:3], v[106:107]
	v_mov_b64_e32 v[10:11], v[106:107]
	v_mov_b64_e32 v[18:19], v[106:107]
	v_mov_b64_e32 v[58:59], v[106:107]
	v_mov_b64_e32 v[26:27], v[106:107]
	v_mov_b64_e32 v[34:35], v[106:107]
	v_mov_b64_e32 v[42:43], v[106:107]
	v_mov_b64_e32 v[112:113], v[108:109]
	v_mov_b64_e32 v[6:7], v[106:107]
	v_mov_b64_e32 v[14:15], v[106:107]
	v_mov_b64_e32 v[22:23], v[106:107]
	v_mov_b64_e32 v[62:63], v[106:107]
	v_mov_b64_e32 v[30:31], v[106:107]
	v_mov_b64_e32 v[38:39], v[106:107]
	v_mov_b64_e32 v[46:47], v[106:107]
	v_mov_b64_e32 v[4:5], v[108:109]
	v_mov_b64_e32 v[12:13], v[108:109]
	v_mov_b64_e32 v[20:21], v[108:109]
	v_mov_b64_e32 v[60:61], v[108:109]
	v_mov_b64_e32 v[28:29], v[108:109]
	v_mov_b64_e32 v[36:37], v[108:109]
	v_mov_b64_e32 v[44:45], v[108:109]
	v_mov_b64_e32 v[110:111], v[106:107]
	v_mov_b64_e32 v[8:9], v[108:109]
	v_mov_b64_e32 v[16:17], v[108:109]
	v_mov_b64_e32 v[24:25], v[108:109]
	v_mov_b64_e32 v[64:65], v[108:109]
	v_mov_b64_e32 v[32:33], v[108:109]
	v_mov_b64_e32 v[40:41], v[108:109]
	v_mov_b64_e32 v[48:49], v[108:109]
